# final RMSNorm pass: rolling prefetch, next iteration's first 8 row loads issued mid-iteration into consumed registers
# speedup vs baseline: 1.0250x; 1.0001x over previous
.LBB0_581:
	v_lshlrev_b32_e32 v16, 2, v186
	s_barrier
	s_waitcnt lgkmcnt(0)
	s_barrier
	global_load_dwordx4 v[0:3], v16, s[76:77] offset:16
	global_load_dwordx4 v[4:7], v16, s[76:77]
	global_load_dwordx4 v[8:11], v16, s[76:77] offset:2064
	global_load_dwordx4 v[12:15], v16, s[76:77] offset:2048
	s_lshl_b32 s0, s33, 2
	s_and_b32 s0, s0, 0xffffff80
	s_add_i32 s0, s0, 0
	s_add_i32 s14, s0, 0x20400
	s_lshl_b64 s[0:1], s[86:87], 20
	s_lshl_b64 s[2:3], s[4:5], 12
	s_add_u32 s0, s0, s2
	s_addc_u32 s1, s1, s3
	s_add_u32 s0, s78, s0
	v_lshlrev_b32_e32 v16, 5, v188
	v_mov_b32_e32 v17, 0
	s_addc_u32 s1, s79, s1
	v_lshl_add_u64 v[20:21], s[0:1], 0, v[16:17]
	v_lshl_add_u64 v[22:23], s[80:81], 0, v[184:185]
	s_mov_b64 s[12:13], 0
	v_mov_b32_e32 v46, 0x358637bd
	s_mov_b32 s15, 0x800000
	s_brev_b32 s16, 56
	s_movk_i32 s17, 0x1000
	s_mov_b32 s18, 0x1c001000
	s_movk_i32 s19, 0x2000
	s_movk_i32 s20, 0x3000
	s_mov_b32 s21, 0x1c002000
	s_movk_i32 s22, 0x4000
	s_movk_i32 s23, 0x5000
	s_mov_b32 s24, 0x1c003000
	s_movk_i32 s25, 0x6000
	s_movk_i32 s26, 0x7000
	s_mov_b32 s28, s16
	s_mov_b32 s29, 0
	s_mov_b32 s30, s18
	s_mov_b32 s31, 0
	v_lshl_add_u64 v[144:145], v[22:23], 0, s[10:11]
	v_lshl_add_u64 v[146:147], v[144:145], 0, s[28:29]
	v_lshl_add_u64 v[148:149], v[144:145], 0, s[30:31]
	global_load_dwordx4 v[80:83], v[148:149], off offset:-4096
	global_load_dwordx4 v[84:87], v[146:147], off offset:1024
	global_load_dwordx4 v[88:91], v[146:147], off offset:2048
	global_load_dwordx4 v[92:95], v[146:147], off offset:3072
	global_load_dwordx4 v[96:99], v[148:149], off
	global_load_dwordx4 v[100:103], v[148:149], off offset:1024
	global_load_dwordx4 v[104:107], v[148:149], off offset:2048
	global_load_dwordx4 v[108:111], v[148:149], off offset:3072
.LBB0_582:
	s_nop 0
	v_lshl_add_u64 v[32:33], v[22:23], 0, s[10:11]
	v_add_co_u32_e32 v28, vcc, s16, v32
	v_mov_b32_e32 v16, s14
	s_nop 0
	v_addc_co_u32_e32 v29, vcc, 0, v33, vcc
	v_add_co_u32_e32 v64, vcc, s18, v32
	ds_read_b128 v[48:51], v16
	ds_read_b128 v[16:19], v16 offset:16
	v_addc_co_u32_e32 v65, vcc, 0, v33, vcc
	v_lshl_add_u64 v[24:25], v[20:21], 0, s[12:13]
	v_add_co_u32_e64 v34, s[0:1], s17, v24
	s_waitcnt lgkmcnt(1)
	v_fmamk_f32 v47, v50, 0x3a800000, v46
	v_addc_co_u32_e64 v35, s[0:1], 0, v25, s[0:1]
	v_add_co_u32_e64 v30, s[0:1], s19, v24
	s_waitcnt lgkmcnt(0)
	v_fmamk_f32 v16, v16, 0x3a800000, v46
	v_addc_co_u32_e64 v31, s[0:1], 0, v25, s[0:1]
	v_add_co_u32_e64 v40, s[0:1], s20, v24
	v_fmamk_f32 v17, v17, 0x3a800000, v46
	s_nop 0
	v_addc_co_u32_e64 v41, s[0:1], 0, v25, s[0:1]
	v_add_co_u32_e64 v36, s[0:1], s22, v24
	v_mul_f32_e32 v61, 0x4b800000, v16
	s_nop 0
	v_addc_co_u32_e64 v37, s[0:1], 0, v25, s[0:1]
	v_add_co_u32_e64 v42, s[0:1], s21, v32
	v_cmp_gt_f32_e64 s[4:5], s15, v16
	s_nop 0
	v_addc_co_u32_e64 v43, s[0:1], 0, v33, s[0:1]
	v_add_co_u32_e64 v26, s[0:1], s24, v32
	v_fmamk_f32 v32, v48, 0x3a800000, v46
	s_nop 0
	v_addc_co_u32_e64 v27, s[0:1], 0, v33, s[0:1]
	v_add_co_u32_e64 v44, s[0:1], s23, v24
	v_fmamk_f32 v33, v49, 0x3a800000, v46
	s_nop 0
	v_addc_co_u32_e64 v45, s[0:1], 0, v25, s[0:1]
	v_add_co_u32_e64 v38, s[0:1], s25, v24
	v_fmamk_f32 v48, v51, 0x3a800000, v46
	s_nop 0
	v_addc_co_u32_e64 v39, s[0:1], 0, v25, s[0:1]
	v_mul_f32_e32 v49, 0x4b800000, v32
	v_mul_f32_e32 v50, 0x4b800000, v33
	v_cmp_gt_f32_e32 vcc, s15, v33
	v_mul_f32_e32 v51, 0x4b800000, v47
	v_cmp_gt_f32_e64 s[0:1], s15, v47
	v_mul_f32_e32 v60, 0x4b800000, v48
	v_cmp_gt_f32_e64 s[2:3], s15, v48
	v_cmp_gt_f32_e64 s[8:9], s15, v32
	v_mul_f32_e32 v62, 0x4b800000, v17
	v_cmp_gt_f32_e64 s[6:7], s15, v17
	v_cndmask_b32_e64 v32, v32, v49, s[8:9]
	v_cndmask_b32_e32 v33, v33, v50, vcc
	v_cndmask_b32_e64 v47, v47, v51, s[0:1]
	v_cndmask_b32_e64 v48, v48, v60, s[2:3]
	v_cndmask_b32_e64 v16, v16, v61, s[4:5]
	v_cndmask_b32_e64 v17, v17, v62, s[6:7]
	v_rsq_f32_e32 v32, v32
	v_rsq_f32_e32 v33, v33
	v_rsq_f32_e32 v47, v47
	v_rsq_f32_e32 v48, v48
	v_rsq_f32_e32 v49, v16
	v_rsq_f32_e32 v17, v17
	v_mul_f32_e32 v16, 0x45800000, v32
	v_mul_f32_e32 v50, 0x45800000, v33
	v_mul_f32_e32 v51, 0x45800000, v47
	v_mul_f32_e32 v60, 0x45800000, v48
	v_mul_f32_e32 v61, 0x45800000, v49
	v_mul_f32_e32 v62, 0x45800000, v17
	v_cndmask_b32_e64 v16, v32, v16, s[8:9]
	v_cndmask_b32_e32 v32, v33, v50, vcc
	v_cndmask_b32_e64 v66, v47, v51, s[0:1]
	v_cndmask_b32_e64 v68, v48, v60, s[2:3]
	v_cndmask_b32_e64 v70, v49, v61, s[4:5]
	v_cndmask_b32_e64 v72, v17, v62, s[6:7]
	s_add_i32 s14, s14, 32
	s_add_u32 s12, s12, 0x8000
	s_addc_u32 s13, s13, 0
	global_load_dwordx4 v[112:115], v[26:27], off offset:-4096
	global_load_dwordx4 v[116:119], v[42:43], off offset:1024
	global_load_dwordx4 v[120:123], v[42:43], off offset:2048
	global_load_dwordx4 v[124:127], v[42:43], off offset:3072
	global_load_dwordx4 v[128:131], v[26:27], off
	global_load_dwordx4 v[132:135], v[26:27], off offset:1024
	global_load_dwordx4 v[136:139], v[26:27], off offset:2048
	global_load_dwordx4 v[140:143], v[26:27], off offset:3072
	s_waitcnt vmcnt(15)
	v_lshlrev_b32_e32 v48, 16, v80
	v_and_b32_e32 v49, 0xffff0000, v80
	v_lshlrev_b32_e32 v50, 16, v81
	v_and_b32_e32 v51, 0xffff0000, v81
	v_lshlrev_b32_e32 v52, 16, v82
	v_and_b32_e32 v53, 0xffff0000, v82
	v_lshlrev_b32_e32 v54, 16, v83
	v_and_b32_e32 v55, 0xffff0000, v83
	s_waitcnt vmcnt(14)
	v_lshlrev_b32_e32 v60, 16, v84
	v_and_b32_e32 v61, 0xffff0000, v84
	v_lshlrev_b32_e32 v56, 16, v85
	v_and_b32_e32 v57, 0xffff0000, v85
	v_lshlrev_b32_e32 v62, 16, v86
	v_and_b32_e32 v63, 0xffff0000, v86
	v_lshlrev_b32_e32 v58, 16, v87
	v_and_b32_e32 v59, 0xffff0000, v87
	v_pk_mul_f32 v[48:49], v[16:17], v[48:49] op_sel_hi:[0,1]
	v_pk_mul_f32 v[50:51], v[16:17], v[50:51] op_sel_hi:[0,1]
	v_pk_mul_f32 v[52:53], v[16:17], v[52:53] op_sel_hi:[0,1]
	v_pk_mul_f32 v[54:55], v[16:17], v[54:55] op_sel_hi:[0,1]
	v_pk_mul_f32 v[60:61], v[16:17], v[60:61] op_sel_hi:[0,1]
	v_pk_mul_f32 v[56:57], v[16:17], v[56:57] op_sel_hi:[0,1]
	v_pk_mul_f32 v[74:75], v[16:17], v[62:63] op_sel_hi:[0,1]
	v_pk_mul_f32 v[16:17], v[16:17], v[58:59] op_sel_hi:[0,1]
	v_pk_mul_f32 v[50:51], v[6:7], v[50:51]
	v_pk_mul_f32 v[48:49], v[4:5], v[48:49]
	v_pk_mul_f32 v[54:55], v[2:3], v[54:55]
	v_pk_mul_f32 v[52:53], v[0:1], v[52:53]
	v_pk_mul_f32 v[58:59], v[14:15], v[56:57]
	v_pk_mul_f32 v[56:57], v[12:13], v[60:61]
	v_pk_mul_f32 v[62:63], v[10:11], v[16:17]
	v_pk_mul_f32 v[60:61], v[8:9], v[74:75]
	global_store_dwordx4 v[24:25], v[48:51], off
	global_store_dwordx4 v[24:25], v[52:55], off offset:16
	global_store_dwordx4 v[24:25], v[56:59], off offset:2048
	global_store_dwordx4 v[24:25], v[60:63], off offset:2064
	s_nop 0
	s_add_u32 s10, s10, 0x4000
	s_addc_u32 s11, s11, 0
	s_cmp_lg_u32 s12, 0x20000
	s_waitcnt vmcnt(17)
	v_lshlrev_b32_e32 v16, 16, v88
	v_and_b32_e32 v17, 0xffff0000, v88
	v_lshlrev_b32_e32 v28, 16, v89
	v_and_b32_e32 v29, 0xffff0000, v89
	v_lshlrev_b32_e32 v48, 16, v90
	v_and_b32_e32 v49, 0xffff0000, v90
	v_lshlrev_b32_e32 v50, 16, v91
	v_and_b32_e32 v51, 0xffff0000, v91
	s_waitcnt vmcnt(16)
	v_lshlrev_b32_e32 v56, 16, v92
	v_and_b32_e32 v57, 0xffff0000, v92
	v_lshlrev_b32_e32 v52, 16, v93
	v_and_b32_e32 v53, 0xffff0000, v93
	v_lshlrev_b32_e32 v58, 16, v94
	v_and_b32_e32 v59, 0xffff0000, v94
	v_lshlrev_b32_e32 v54, 16, v95
	v_and_b32_e32 v55, 0xffff0000, v95
	v_pk_mul_f32 v[16:17], v[32:33], v[16:17] op_sel_hi:[0,1]
	v_pk_mul_f32 v[28:29], v[32:33], v[28:29] op_sel_hi:[0,1]
	v_pk_mul_f32 v[60:61], v[32:33], v[48:49] op_sel_hi:[0,1]
	v_pk_mul_f32 v[62:63], v[32:33], v[50:51] op_sel_hi:[0,1]
	v_pk_mul_f32 v[56:57], v[32:33], v[56:57] op_sel_hi:[0,1]
	v_pk_mul_f32 v[74:75], v[32:33], v[52:53] op_sel_hi:[0,1]
	v_pk_mul_f32 v[76:77], v[32:33], v[58:59] op_sel_hi:[0,1]
	v_pk_mul_f32 v[32:33], v[32:33], v[54:55] op_sel_hi:[0,1]
	v_pk_mul_f32 v[50:51], v[6:7], v[28:29]
	v_pk_mul_f32 v[48:49], v[4:5], v[16:17]
	v_pk_mul_f32 v[54:55], v[2:3], v[62:63]
	v_pk_mul_f32 v[52:53], v[0:1], v[60:61]
	v_pk_mul_f32 v[58:59], v[14:15], v[74:75]
	v_pk_mul_f32 v[56:57], v[12:13], v[56:57]
	v_pk_mul_f32 v[62:63], v[10:11], v[32:33]
	v_pk_mul_f32 v[60:61], v[8:9], v[76:77]
	global_store_dwordx4 v[30:31], v[48:51], off offset:-4096
	global_store_dwordx4 v[34:35], v[52:55], off offset:16
	global_store_dwordx4 v[34:35], v[56:59], off offset:2048
	global_store_dwordx4 v[34:35], v[60:63], off offset:2064
	s_nop 0
	s_waitcnt vmcnt(19)
	v_lshlrev_b32_e32 v16, 16, v96
	v_and_b32_e32 v17, 0xffff0000, v96
	v_lshlrev_b32_e32 v28, 16, v97
	v_and_b32_e32 v29, 0xffff0000, v97
	v_lshlrev_b32_e32 v32, 16, v98
	v_and_b32_e32 v33, 0xffff0000, v98
	v_lshlrev_b32_e32 v34, 16, v99
	v_and_b32_e32 v35, 0xffff0000, v99
	s_waitcnt vmcnt(18)
	v_lshlrev_b32_e32 v52, 16, v100
	v_and_b32_e32 v53, 0xffff0000, v100
	v_lshlrev_b32_e32 v48, 16, v101
	v_and_b32_e32 v49, 0xffff0000, v101
	v_lshlrev_b32_e32 v54, 16, v102
	v_and_b32_e32 v55, 0xffff0000, v102
	v_lshlrev_b32_e32 v50, 16, v103
	v_and_b32_e32 v51, 0xffff0000, v103
	v_pk_mul_f32 v[16:17], v[66:67], v[16:17] op_sel_hi:[0,1]
	v_pk_mul_f32 v[28:29], v[66:67], v[28:29] op_sel_hi:[0,1]
	v_pk_mul_f32 v[56:57], v[66:67], v[32:33] op_sel_hi:[0,1]
	v_pk_mul_f32 v[58:59], v[66:67], v[34:35] op_sel_hi:[0,1]
	v_pk_mul_f32 v[52:53], v[66:67], v[52:53] op_sel_hi:[0,1]
	v_pk_mul_f32 v[60:61], v[66:67], v[48:49] op_sel_hi:[0,1]
	v_pk_mul_f32 v[62:63], v[66:67], v[54:55] op_sel_hi:[0,1]
	v_pk_mul_f32 v[66:67], v[66:67], v[50:51] op_sel_hi:[0,1]
	v_pk_mul_f32 v[34:35], v[6:7], v[28:29]
	v_pk_mul_f32 v[32:33], v[4:5], v[16:17]
	v_pk_mul_f32 v[50:51], v[2:3], v[58:59]
	v_pk_mul_f32 v[48:49], v[0:1], v[56:57]
	v_pk_mul_f32 v[54:55], v[14:15], v[60:61]
	v_pk_mul_f32 v[52:53], v[12:13], v[52:53]
	v_pk_mul_f32 v[58:59], v[10:11], v[66:67]
	v_pk_mul_f32 v[56:57], v[8:9], v[62:63]
	global_store_dwordx4 v[30:31], v[32:35], off
	global_store_dwordx4 v[30:31], v[48:51], off offset:16
	global_store_dwordx4 v[30:31], v[52:55], off offset:2048
	global_store_dwordx4 v[30:31], v[56:59], off offset:2064
	s_nop 0
	s_waitcnt vmcnt(21)
	v_lshlrev_b32_e32 v16, 16, v104
	v_and_b32_e32 v17, 0xffff0000, v104
	v_lshlrev_b32_e32 v28, 16, v105
	v_and_b32_e32 v29, 0xffff0000, v105
	v_lshlrev_b32_e32 v48, 16, v106
	v_and_b32_e32 v49, 0xffff0000, v106
	v_lshlrev_b32_e32 v30, 16, v107
	v_and_b32_e32 v31, 0xffff0000, v107
	s_waitcnt vmcnt(20)
	v_lshlrev_b32_e32 v50, 16, v108
	v_and_b32_e32 v51, 0xffff0000, v108
	v_lshlrev_b32_e32 v32, 16, v109
	v_and_b32_e32 v33, 0xffff0000, v109
	v_lshlrev_b32_e32 v52, 16, v110
	v_and_b32_e32 v53, 0xffff0000, v110
	v_lshlrev_b32_e32 v34, 16, v111
	v_and_b32_e32 v35, 0xffff0000, v111
	v_pk_mul_f32 v[16:17], v[68:69], v[16:17] op_sel_hi:[0,1]
	v_pk_mul_f32 v[28:29], v[68:69], v[28:29] op_sel_hi:[0,1]
	v_pk_mul_f32 v[48:49], v[68:69], v[48:49] op_sel_hi:[0,1]
	v_pk_mul_f32 v[54:55], v[68:69], v[30:31] op_sel_hi:[0,1]
	v_pk_mul_f32 v[56:57], v[68:69], v[50:51] op_sel_hi:[0,1]
	v_pk_mul_f32 v[50:51], v[68:69], v[32:33] op_sel_hi:[0,1]
	v_pk_mul_f32 v[52:53], v[68:69], v[52:53] op_sel_hi:[0,1]
	v_pk_mul_f32 v[58:59], v[68:69], v[34:35] op_sel_hi:[0,1]
	v_pk_mul_f32 v[30:31], v[6:7], v[28:29]
	v_pk_mul_f32 v[28:29], v[4:5], v[16:17]
	v_pk_mul_f32 v[34:35], v[2:3], v[54:55]
	v_pk_mul_f32 v[32:33], v[0:1], v[48:49]
	v_pk_mul_f32 v[50:51], v[14:15], v[50:51]
	v_pk_mul_f32 v[48:49], v[12:13], v[56:57]
	v_pk_mul_f32 v[54:55], v[10:11], v[58:59]
	v_pk_mul_f32 v[52:53], v[8:9], v[52:53]
	global_store_dwordx4 v[36:37], v[28:31], off offset:-4096
	global_store_dwordx4 v[40:41], v[32:35], off offset:16
	global_store_dwordx4 v[40:41], v[48:51], off offset:2048
	global_store_dwordx4 v[40:41], v[52:55], off offset:2064
	s_cbranch_scc0 .Lmy_np_skip
	v_lshl_add_u64 v[144:145], v[22:23], 0, s[10:11]
	v_lshl_add_u64 v[146:147], v[144:145], 0, s[28:29]
	v_lshl_add_u64 v[148:149], v[144:145], 0, s[30:31]
	global_load_dwordx4 v[80:83], v[148:149], off offset:-4096
	global_load_dwordx4 v[84:87], v[146:147], off offset:1024
	global_load_dwordx4 v[88:91], v[146:147], off offset:2048
	global_load_dwordx4 v[92:95], v[146:147], off offset:3072
	global_load_dwordx4 v[96:99], v[148:149], off
	global_load_dwordx4 v[100:103], v[148:149], off offset:1024
	global_load_dwordx4 v[104:107], v[148:149], off offset:2048
	global_load_dwordx4 v[108:111], v[148:149], off offset:3072
.Lmy_np_skip:
	s_nop 0
	s_waitcnt vmcnt(23)
	v_lshlrev_b32_e32 v16, 16, v112
	v_and_b32_e32 v17, 0xffff0000, v112
	v_lshlrev_b32_e32 v28, 16, v113
	v_and_b32_e32 v29, 0xffff0000, v113
	v_lshlrev_b32_e32 v40, 16, v114
	v_and_b32_e32 v41, 0xffff0000, v114
	v_lshlrev_b32_e32 v30, 16, v115
	v_and_b32_e32 v31, 0xffff0000, v115
	s_waitcnt vmcnt(22)
	v_lshlrev_b32_e32 v48, 16, v116
	v_and_b32_e32 v49, 0xffff0000, v116
	v_lshlrev_b32_e32 v32, 16, v117
	v_and_b32_e32 v33, 0xffff0000, v117
	v_lshlrev_b32_e32 v50, 16, v118
	v_and_b32_e32 v51, 0xffff0000, v118
	v_lshlrev_b32_e32 v34, 16, v119
	v_and_b32_e32 v35, 0xffff0000, v119
	v_pk_mul_f32 v[16:17], v[70:71], v[16:17] op_sel_hi:[0,1]
	v_pk_mul_f32 v[28:29], v[70:71], v[28:29] op_sel_hi:[0,1]
	v_pk_mul_f32 v[40:41], v[70:71], v[40:41] op_sel_hi:[0,1]
	v_pk_mul_f32 v[52:53], v[70:71], v[30:31] op_sel_hi:[0,1]
	v_pk_mul_f32 v[48:49], v[70:71], v[48:49] op_sel_hi:[0,1]
	v_pk_mul_f32 v[54:55], v[70:71], v[32:33] op_sel_hi:[0,1]
	v_pk_mul_f32 v[56:57], v[70:71], v[50:51] op_sel_hi:[0,1]
	v_pk_mul_f32 v[58:59], v[70:71], v[34:35] op_sel_hi:[0,1]
	v_pk_mul_f32 v[30:31], v[6:7], v[28:29]
	v_pk_mul_f32 v[28:29], v[4:5], v[16:17]
	v_pk_mul_f32 v[34:35], v[2:3], v[52:53]
	v_pk_mul_f32 v[32:33], v[0:1], v[40:41]
	v_pk_mul_f32 v[50:51], v[14:15], v[54:55]
	v_pk_mul_f32 v[48:49], v[12:13], v[48:49]
	v_pk_mul_f32 v[54:55], v[10:11], v[58:59]
	v_pk_mul_f32 v[52:53], v[8:9], v[56:57]
	global_store_dwordx4 v[36:37], v[28:31], off
	global_store_dwordx4 v[36:37], v[32:35], off offset:16
	global_store_dwordx4 v[36:37], v[48:51], off offset:2048
	global_store_dwordx4 v[36:37], v[52:55], off offset:2064
	s_nop 0
	s_waitcnt vmcnt(25)
	v_lshlrev_b32_e32 v16, 16, v120
	v_and_b32_e32 v17, 0xffff0000, v120
	v_lshlrev_b32_e32 v28, 16, v121
	v_and_b32_e32 v29, 0xffff0000, v121
	v_lshlrev_b32_e32 v36, 16, v122
	v_and_b32_e32 v37, 0xffff0000, v122
	v_lshlrev_b32_e32 v30, 16, v123
	v_and_b32_e32 v31, 0xffff0000, v123
	s_waitcnt vmcnt(24)
	v_lshlrev_b32_e32 v40, 16, v124
	v_and_b32_e32 v41, 0xffff0000, v124
	v_lshlrev_b32_e32 v32, 16, v125
	v_and_b32_e32 v33, 0xffff0000, v125
	v_lshlrev_b32_e32 v42, 16, v126
	v_and_b32_e32 v43, 0xffff0000, v126
	v_lshlrev_b32_e32 v34, 16, v127
	v_and_b32_e32 v35, 0xffff0000, v127
	v_pk_mul_f32 v[16:17], v[72:73], v[16:17] op_sel_hi:[0,1]
	v_pk_mul_f32 v[28:29], v[72:73], v[28:29] op_sel_hi:[0,1]
	v_pk_mul_f32 v[36:37], v[72:73], v[36:37] op_sel_hi:[0,1]
	v_pk_mul_f32 v[48:49], v[72:73], v[30:31] op_sel_hi:[0,1]
	v_pk_mul_f32 v[40:41], v[72:73], v[40:41] op_sel_hi:[0,1]
	v_pk_mul_f32 v[50:51], v[72:73], v[32:33] op_sel_hi:[0,1]
	v_pk_mul_f32 v[52:53], v[72:73], v[42:43] op_sel_hi:[0,1]
	v_pk_mul_f32 v[54:55], v[72:73], v[34:35] op_sel_hi:[0,1]
	v_pk_mul_f32 v[30:31], v[6:7], v[28:29]
	v_pk_mul_f32 v[28:29], v[4:5], v[16:17]
	v_pk_mul_f32 v[34:35], v[2:3], v[48:49]
	v_pk_mul_f32 v[32:33], v[0:1], v[36:37]
	v_pk_mul_f32 v[42:43], v[14:15], v[50:51]
	v_pk_mul_f32 v[40:41], v[12:13], v[40:41]
	v_pk_mul_f32 v[50:51], v[10:11], v[54:55]
	v_pk_mul_f32 v[48:49], v[8:9], v[52:53]
	global_store_dwordx4 v[38:39], v[28:31], off offset:-4096
	global_store_dwordx4 v[44:45], v[32:35], off offset:16
	global_store_dwordx4 v[44:45], v[40:43], off offset:2048
	global_store_dwordx4 v[44:45], v[48:51], off offset:2064
	s_nop 0
	v_fmamk_f32 v16, v18, 0x3a800000, v46
	v_mul_f32_e32 v17, 0x4b800000, v16
	v_cmp_gt_f32_e32 vcc, s15, v16
	s_waitcnt vmcnt(27)
	v_lshlrev_b32_e32 v36, 16, v128
	v_cndmask_b32_e32 v16, v16, v17, vcc
	v_rsq_f32_e32 v16, v16
	v_and_b32_e32 v37, 0xffff0000, v128
	v_lshlrev_b32_e32 v28, 16, v129
	v_and_b32_e32 v29, 0xffff0000, v129
	v_mul_f32_e32 v17, 0x45800000, v16
	v_cndmask_b32_e32 v16, v16, v17, vcc
	v_lshlrev_b32_e32 v40, 16, v130
	v_and_b32_e32 v41, 0xffff0000, v130
	v_lshlrev_b32_e32 v30, 16, v131
	v_and_b32_e32 v31, 0xffff0000, v131
	s_waitcnt vmcnt(26)
	v_lshlrev_b32_e32 v42, 16, v132
	v_and_b32_e32 v43, 0xffff0000, v132
	v_lshlrev_b32_e32 v32, 16, v133
	v_and_b32_e32 v33, 0xffff0000, v133
	v_lshlrev_b32_e32 v44, 16, v134
	v_and_b32_e32 v45, 0xffff0000, v134
	v_lshlrev_b32_e32 v34, 16, v135
	v_and_b32_e32 v35, 0xffff0000, v135
	v_pk_mul_f32 v[36:37], v[16:17], v[36:37] op_sel_hi:[0,1]
	v_pk_mul_f32 v[28:29], v[16:17], v[28:29] op_sel_hi:[0,1]
	v_pk_mul_f32 v[40:41], v[16:17], v[40:41] op_sel_hi:[0,1]
	v_pk_mul_f32 v[48:49], v[16:17], v[30:31] op_sel_hi:[0,1]
	v_pk_mul_f32 v[50:51], v[16:17], v[42:43] op_sel_hi:[0,1]
	v_pk_mul_f32 v[42:43], v[16:17], v[32:33] op_sel_hi:[0,1]
	v_pk_mul_f32 v[44:45], v[16:17], v[44:45] op_sel_hi:[0,1]
	v_pk_mul_f32 v[16:17], v[16:17], v[34:35] op_sel_hi:[0,1]
	v_pk_mul_f32 v[30:31], v[6:7], v[28:29]
	v_pk_mul_f32 v[28:29], v[4:5], v[36:37]
	v_pk_mul_f32 v[34:35], v[2:3], v[48:49]
	v_pk_mul_f32 v[32:33], v[0:1], v[40:41]
	v_pk_mul_f32 v[42:43], v[14:15], v[42:43]
	v_pk_mul_f32 v[40:41], v[12:13], v[50:51]
	v_pk_mul_f32 v[50:51], v[10:11], v[16:17]
	v_pk_mul_f32 v[48:49], v[8:9], v[44:45]
	global_store_dwordx4 v[38:39], v[28:31], off
	global_store_dwordx4 v[38:39], v[32:35], off offset:16
	global_store_dwordx4 v[38:39], v[40:43], off offset:2048
	global_store_dwordx4 v[38:39], v[48:51], off offset:2064
	s_nop 0
	v_add_co_u32_e32 v36, vcc, s26, v24
	v_fmamk_f32 v16, v19, 0x3a800000, v46
	s_nop 0
	v_addc_co_u32_e32 v37, vcc, 0, v25, vcc
	v_mul_f32_e32 v17, 0x4b800000, v16
	v_cmp_gt_f32_e32 vcc, s15, v16
	s_waitcnt vmcnt(29)
	v_lshlrev_b32_e32 v18, 16, v136
	v_cndmask_b32_e32 v16, v16, v17, vcc
	v_rsq_f32_e32 v16, v16
	v_and_b32_e32 v19, 0xffff0000, v136
	v_lshlrev_b32_e32 v24, 16, v137
	v_and_b32_e32 v25, 0xffff0000, v137
	v_mul_f32_e32 v17, 0x45800000, v16
	v_cndmask_b32_e32 v16, v16, v17, vcc
	v_lshlrev_b32_e32 v26, 16, v138
	v_and_b32_e32 v27, 0xffff0000, v138
	v_lshlrev_b32_e32 v28, 16, v139
	v_and_b32_e32 v29, 0xffff0000, v139
	s_waitcnt vmcnt(28)
	v_lshlrev_b32_e32 v30, 16, v140
	v_and_b32_e32 v31, 0xffff0000, v140
	v_lshlrev_b32_e32 v32, 16, v141
	v_and_b32_e32 v33, 0xffff0000, v141
	v_lshlrev_b32_e32 v38, 16, v142
	v_and_b32_e32 v39, 0xffff0000, v142
	v_lshlrev_b32_e32 v34, 16, v143
	v_and_b32_e32 v35, 0xffff0000, v143
	v_pk_mul_f32 v[40:41], v[16:17], v[18:19] op_sel_hi:[0,1]
	v_pk_mul_f32 v[18:19], v[16:17], v[24:25] op_sel_hi:[0,1]
	v_pk_mul_f32 v[24:25], v[16:17], v[26:27] op_sel_hi:[0,1]
	v_pk_mul_f32 v[26:27], v[16:17], v[28:29] op_sel_hi:[0,1]
	v_pk_mul_f32 v[28:29], v[16:17], v[30:31] op_sel_hi:[0,1]
	v_pk_mul_f32 v[30:31], v[16:17], v[32:33] op_sel_hi:[0,1]
	v_pk_mul_f32 v[32:33], v[16:17], v[38:39] op_sel_hi:[0,1]
	v_pk_mul_f32 v[34:35], v[16:17], v[34:35] op_sel_hi:[0,1]
	v_pk_mul_f32 v[18:19], v[6:7], v[18:19]
	v_pk_mul_f32 v[16:17], v[4:5], v[40:41]
	v_pk_mul_f32 v[26:27], v[2:3], v[26:27]
	v_pk_mul_f32 v[24:25], v[0:1], v[24:25]
	v_pk_mul_f32 v[30:31], v[14:15], v[30:31]
	v_pk_mul_f32 v[28:29], v[12:13], v[28:29]
	v_pk_mul_f32 v[34:35], v[10:11], v[34:35]
	v_pk_mul_f32 v[32:33], v[8:9], v[32:33]
	global_store_dwordx4 v[36:37], v[16:19], off
	global_store_dwordx4 v[36:37], v[24:27], off offset:16
	global_store_dwordx4 v[36:37], v[28:31], off offset:2048
	global_store_dwordx4 v[36:37], v[32:35], off offset:2064
	s_cbranch_scc1 .LBB0_582
	s_endpgm
